# skinny NC=2 GEMM steps: 12 fragment ds_reads issued ahead, MFMAs on counted lgkmcnt (9 sections); on top of v034
# speedup vs baseline: 1.0086x; 1.0086x over previous
.LBB0_251:
	v_add_u32_e32 v156, s8, v194
	v_add_u32_e32 v157, s8, v195
	v_add_u32_e32 v158, v156, v207
	ds_read_b128 v[216:219], v158
	v_add_u32_e32 v159, v157, v207
	ds_read_b128 v[232:235], v159 offset:32768
	ds_read_b128 v[244:247], v159 offset:49152
	v_add_u32_e32 v164, v156, v208
	ds_read_b128 v[220:223], v164
	v_add_u32_e32 v165, v157, v208
	ds_read_b128 v[236:239], v165 offset:32768
	ds_read_b128 v[248:251], v165 offset:49152
	v_add_u32_e32 v180, v156, v209
	ds_read_b128 v[224:227], v180
	v_add_u32_e32 v181, v157, v209
	ds_read_b128 v[240:243], v181 offset:32768
	ds_read_b128 v[176:179], v181 offset:49152
	v_add_u32_e32 v200, v156, v210
	ds_read_b128 v[228:231], v200
	v_add_u32_e32 v201, v157, v210
	s_waitcnt lgkmcnt(8)
	v_mfma_f32_32x32x16_bf16 v[4:19], v[232:235], v[216:219], v[4:19]
	s_waitcnt lgkmcnt(7)
	v_mfma_f32_32x32x16_bf16 v[20:35], v[244:247], v[216:219], v[20:35]
	ds_read_b128 v[232:235], v201 offset:32768
	ds_read_b128 v[244:247], v201 offset:49152
	s_waitcnt lgkmcnt(7)
	v_mfma_f32_32x32x16_bf16 v[4:19], v[236:239], v[220:223], v[4:19]
	s_waitcnt lgkmcnt(6)
	v_mfma_f32_32x32x16_bf16 v[20:35], v[248:251], v[220:223], v[20:35]
	s_waitcnt lgkmcnt(4)
	v_mfma_f32_32x32x16_bf16 v[4:19], v[240:243], v[224:227], v[4:19]
	s_waitcnt lgkmcnt(3)
	v_mfma_f32_32x32x16_bf16 v[20:35], v[176:179], v[224:227], v[20:35]
	s_waitcnt lgkmcnt(1)
	v_mfma_f32_32x32x16_bf16 v[4:19], v[232:235], v[228:231], v[4:19]
	s_waitcnt lgkmcnt(0)
	s_barrier
	v_mfma_f32_32x32x16_bf16 v[20:35], v[244:247], v[228:231], v[20:35]

.LBB0_255:
	s_add_i32 s8, s8, 0
	v_add_u32_e32 v156, s8, v194
	v_add_u32_e32 v157, s8, v195
	s_cmp_lt_u32 s6, 6
	s_cselect_b64 s[18:19], -1, 0
	s_cmp_gt_u32 s6, 5
	v_add_u32_e32 v158, v156, v207
	ds_read_b128 v[216:219], v158
	v_add_u32_e32 v159, v157, v207
	ds_read_b128 v[232:235], v159 offset:32768
	ds_read_b128 v[244:247], v159 offset:49152
	v_add_u32_e32 v164, v156, v208
	ds_read_b128 v[220:223], v164
	v_add_u32_e32 v165, v157, v208
	ds_read_b128 v[236:239], v165 offset:32768
	ds_read_b128 v[248:251], v165 offset:49152
	v_add_u32_e32 v180, v156, v209
	ds_read_b128 v[224:227], v180
	v_add_u32_e32 v181, v157, v209
	ds_read_b128 v[240:243], v181 offset:32768
	ds_read_b128 v[152:155], v181 offset:49152
	v_add_u32_e32 v200, v156, v210
	ds_read_b128 v[228:231], v200
	v_add_u32_e32 v201, v157, v210
	s_waitcnt lgkmcnt(8)
	v_mfma_f32_32x32x16_bf16 v[4:19], v[232:235], v[216:219], v[4:19]
	s_waitcnt lgkmcnt(7)
	v_mfma_f32_32x32x16_bf16 v[20:35], v[244:247], v[216:219], v[20:35]
	ds_read_b128 v[232:235], v201 offset:32768
	ds_read_b128 v[244:247], v201 offset:49152
	s_waitcnt lgkmcnt(7)
	v_mfma_f32_32x32x16_bf16 v[4:19], v[236:239], v[220:223], v[4:19]
	s_waitcnt lgkmcnt(6)
	v_mfma_f32_32x32x16_bf16 v[20:35], v[248:251], v[220:223], v[20:35]
	s_waitcnt lgkmcnt(4)
	v_mfma_f32_32x32x16_bf16 v[4:19], v[240:243], v[224:227], v[4:19]
	s_waitcnt lgkmcnt(3)
	v_mfma_f32_32x32x16_bf16 v[20:35], v[152:155], v[224:227], v[20:35]
	s_waitcnt lgkmcnt(1)
	v_mfma_f32_32x32x16_bf16 v[4:19], v[232:235], v[228:231], v[4:19]
	s_waitcnt lgkmcnt(0)
	s_barrier
	v_mfma_f32_32x32x16_bf16 v[20:35], v[244:247], v[228:231], v[20:35]
	s_cbranch_scc1 .LBB0_257
	v_add_u32_e32 v154, s8, v192
	s_waitcnt vmcnt(8)
	ds_write_b128 v154, v[52:55]
	ds_write_b128 v154, v[64:67] offset:8192
	ds_write_b128 v154, v[68:71] offset:16384
	ds_write_b128 v154, v[88:91] offset:24576
	ds_write_b128 v154, v[116:119] offset:32768
	ds_write_b128 v154, v[120:123] offset:40960
	ds_write_b128 v154, v[124:127] offset:49152
	ds_write_b128 v154, v[128:131] offset:57344

.LBB0_259:
	v_add_u32_e32 v154, s7, v194
	v_add_u32_e32 v155, s7, v195
	s_andn2_b64 vcc, exec, s[18:19]
	v_add_u32_e32 v158, v154, v207
	ds_read_b128 v[216:219], v158
	v_add_u32_e32 v159, v155, v207
	ds_read_b128 v[232:235], v159 offset:32768
	ds_read_b128 v[244:247], v159 offset:49152
	v_add_u32_e32 v164, v154, v208
	ds_read_b128 v[220:223], v164
	v_add_u32_e32 v165, v155, v208
	ds_read_b128 v[236:239], v165 offset:32768
	ds_read_b128 v[248:251], v165 offset:49152
	v_add_u32_e32 v180, v154, v209
	ds_read_b128 v[224:227], v180
	v_add_u32_e32 v181, v155, v209
	ds_read_b128 v[240:243], v181 offset:32768
	ds_read_b128 v[176:179], v181 offset:49152
	v_add_u32_e32 v200, v154, v210
	ds_read_b128 v[228:231], v200
	v_add_u32_e32 v201, v155, v210
	s_waitcnt lgkmcnt(8)
	v_mfma_f32_32x32x16_bf16 v[4:19], v[232:235], v[216:219], v[4:19]
	s_waitcnt lgkmcnt(7)
	v_mfma_f32_32x32x16_bf16 v[20:35], v[244:247], v[216:219], v[20:35]
	ds_read_b128 v[232:235], v201 offset:32768
	ds_read_b128 v[244:247], v201 offset:49152
	s_waitcnt lgkmcnt(7)
	v_mfma_f32_32x32x16_bf16 v[4:19], v[236:239], v[220:223], v[4:19]
	s_waitcnt lgkmcnt(6)
	v_mfma_f32_32x32x16_bf16 v[20:35], v[248:251], v[220:223], v[20:35]
	s_waitcnt lgkmcnt(4)
	v_mfma_f32_32x32x16_bf16 v[4:19], v[240:243], v[224:227], v[4:19]
	s_waitcnt lgkmcnt(3)
	v_mfma_f32_32x32x16_bf16 v[20:35], v[176:179], v[224:227], v[20:35]
	s_waitcnt lgkmcnt(1)
	v_mfma_f32_32x32x16_bf16 v[4:19], v[232:235], v[228:231], v[4:19]
	s_waitcnt lgkmcnt(0)
	s_barrier
	v_mfma_f32_32x32x16_bf16 v[20:35], v[244:247], v[228:231], v[20:35]
	s_cbranch_vccnz .LBB0_252
	s_cmpk_eq_i32 s2, 0xa00
	s_cbranch_scc1 .LBB0_262
	s_waitcnt vmcnt(8)
	ds_write_b128 v2, v[36:39]
	ds_write_b128 v2, v[48:51] offset:8192
	ds_write_b128 v2, v[80:83] offset:16384
	ds_write_b128 v2, v[60:63] offset:24576
	ds_write_b128 v2, v[84:87] offset:32768
	ds_write_b128 v2, v[96:99] offset:40960
	ds_write_b128 v2, v[104:107] offset:49152
	ds_write_b128 v2, v[112:115] offset:57344

.LBB0_2016:
	v_add_u32_e32 v156, s8, v196
	v_add_u32_e32 v157, s8, v197
	v_add_u32_e32 v158, v156, v209
	ds_read_b128 v[216:219], v158
	v_add_u32_e32 v159, v157, v209
	ds_read_b128 v[232:235], v159 offset:32768
	ds_read_b128 v[244:247], v159 offset:49152
	v_add_u32_e32 v164, v156, v210
	ds_read_b128 v[220:223], v164
	v_add_u32_e32 v165, v157, v210
	ds_read_b128 v[236:239], v165 offset:32768
	ds_read_b128 v[248:251], v165 offset:49152
	v_add_u32_e32 v180, v156, v211
	ds_read_b128 v[224:227], v180
	v_add_u32_e32 v181, v157, v211
	ds_read_b128 v[240:243], v181 offset:32768
	ds_read_b128 v[176:179], v181 offset:49152
	v_add_u32_e32 v200, v156, v212
	ds_read_b128 v[228:231], v200
	v_add_u32_e32 v201, v157, v212
	s_waitcnt lgkmcnt(8)
	v_mfma_f32_32x32x16_bf16 v[4:19], v[232:235], v[216:219], v[4:19]
	s_waitcnt lgkmcnt(7)
	v_mfma_f32_32x32x16_bf16 v[20:35], v[244:247], v[216:219], v[20:35]
	ds_read_b128 v[232:235], v201 offset:32768
	ds_read_b128 v[244:247], v201 offset:49152
	s_waitcnt lgkmcnt(7)
	v_mfma_f32_32x32x16_bf16 v[4:19], v[236:239], v[220:223], v[4:19]
	s_waitcnt lgkmcnt(6)
	v_mfma_f32_32x32x16_bf16 v[20:35], v[248:251], v[220:223], v[20:35]
	s_waitcnt lgkmcnt(4)
	v_mfma_f32_32x32x16_bf16 v[4:19], v[240:243], v[224:227], v[4:19]
	s_waitcnt lgkmcnt(3)
	v_mfma_f32_32x32x16_bf16 v[20:35], v[176:179], v[224:227], v[20:35]
	s_waitcnt lgkmcnt(1)
	v_mfma_f32_32x32x16_bf16 v[4:19], v[232:235], v[228:231], v[4:19]
	s_waitcnt lgkmcnt(0)
	s_barrier
	v_mfma_f32_32x32x16_bf16 v[20:35], v[244:247], v[228:231], v[20:35]

.LBB0_2020:
	s_add_i32 s8, s8, 0
	v_add_u32_e32 v156, s8, v196
	v_add_u32_e32 v157, s8, v197
	s_cmp_lt_u32 s6, 6
	s_cselect_b64 s[20:21], -1, 0
	s_cmp_gt_u32 s6, 5
	v_add_u32_e32 v158, v156, v209
	ds_read_b128 v[216:219], v158
	v_add_u32_e32 v159, v157, v209
	ds_read_b128 v[232:235], v159 offset:32768
	ds_read_b128 v[244:247], v159 offset:49152
	v_add_u32_e32 v164, v156, v210
	ds_read_b128 v[220:223], v164
	v_add_u32_e32 v165, v157, v210
	ds_read_b128 v[236:239], v165 offset:32768
	ds_read_b128 v[248:251], v165 offset:49152
	v_add_u32_e32 v180, v156, v211
	ds_read_b128 v[224:227], v180
	v_add_u32_e32 v181, v157, v211
	ds_read_b128 v[240:243], v181 offset:32768
	ds_read_b128 v[152:155], v181 offset:49152
	v_add_u32_e32 v200, v156, v212
	ds_read_b128 v[228:231], v200
	v_add_u32_e32 v201, v157, v212
	s_waitcnt lgkmcnt(8)
	v_mfma_f32_32x32x16_bf16 v[4:19], v[232:235], v[216:219], v[4:19]
	s_waitcnt lgkmcnt(7)
	v_mfma_f32_32x32x16_bf16 v[20:35], v[244:247], v[216:219], v[20:35]
	ds_read_b128 v[232:235], v201 offset:32768
	ds_read_b128 v[244:247], v201 offset:49152
	s_waitcnt lgkmcnt(7)
	v_mfma_f32_32x32x16_bf16 v[4:19], v[236:239], v[220:223], v[4:19]
	s_waitcnt lgkmcnt(6)
	v_mfma_f32_32x32x16_bf16 v[20:35], v[248:251], v[220:223], v[20:35]
	s_waitcnt lgkmcnt(4)
	v_mfma_f32_32x32x16_bf16 v[4:19], v[240:243], v[224:227], v[4:19]
	s_waitcnt lgkmcnt(3)
	v_mfma_f32_32x32x16_bf16 v[20:35], v[152:155], v[224:227], v[20:35]
	s_waitcnt lgkmcnt(1)
	v_mfma_f32_32x32x16_bf16 v[4:19], v[232:235], v[228:231], v[4:19]
	s_waitcnt lgkmcnt(0)
	s_barrier
	v_mfma_f32_32x32x16_bf16 v[20:35], v[244:247], v[228:231], v[20:35]
	s_cbranch_scc1 .LBB0_2022
	v_add_u32_e32 v154, s8, v194
	s_waitcnt vmcnt(8)
	ds_write_b128 v154, v[52:55]
	ds_write_b128 v154, v[64:67] offset:8192
	ds_write_b128 v154, v[68:71] offset:16384
	ds_write_b128 v154, v[88:91] offset:24576
	ds_write_b128 v154, v[116:119] offset:32768
	ds_write_b128 v154, v[120:123] offset:40960
	ds_write_b128 v154, v[124:127] offset:49152
	ds_write_b128 v154, v[128:131] offset:57344

.LBB0_2024:
	v_add_u32_e32 v154, s7, v196
	v_add_u32_e32 v155, s7, v197
	s_andn2_b64 vcc, exec, s[20:21]
	v_add_u32_e32 v158, v154, v209
	ds_read_b128 v[216:219], v158
	v_add_u32_e32 v159, v155, v209
	ds_read_b128 v[232:235], v159 offset:32768
	ds_read_b128 v[244:247], v159 offset:49152
	v_add_u32_e32 v164, v154, v210
	ds_read_b128 v[220:223], v164
	v_add_u32_e32 v165, v155, v210
	ds_read_b128 v[236:239], v165 offset:32768
	ds_read_b128 v[248:251], v165 offset:49152
	v_add_u32_e32 v180, v154, v211
	ds_read_b128 v[224:227], v180
	v_add_u32_e32 v181, v155, v211
	ds_read_b128 v[240:243], v181 offset:32768
	ds_read_b128 v[176:179], v181 offset:49152
	v_add_u32_e32 v200, v154, v212
	ds_read_b128 v[228:231], v200
	v_add_u32_e32 v201, v155, v212
	s_waitcnt lgkmcnt(8)
	v_mfma_f32_32x32x16_bf16 v[4:19], v[232:235], v[216:219], v[4:19]
	s_waitcnt lgkmcnt(7)
	v_mfma_f32_32x32x16_bf16 v[20:35], v[244:247], v[216:219], v[20:35]
	ds_read_b128 v[232:235], v201 offset:32768
	ds_read_b128 v[244:247], v201 offset:49152
	s_waitcnt lgkmcnt(7)
	v_mfma_f32_32x32x16_bf16 v[4:19], v[236:239], v[220:223], v[4:19]
	s_waitcnt lgkmcnt(6)
	v_mfma_f32_32x32x16_bf16 v[20:35], v[248:251], v[220:223], v[20:35]
	s_waitcnt lgkmcnt(4)
	v_mfma_f32_32x32x16_bf16 v[4:19], v[240:243], v[224:227], v[4:19]
	s_waitcnt lgkmcnt(3)
	v_mfma_f32_32x32x16_bf16 v[20:35], v[176:179], v[224:227], v[20:35]
	s_waitcnt lgkmcnt(1)
	v_mfma_f32_32x32x16_bf16 v[4:19], v[232:235], v[228:231], v[4:19]
	s_waitcnt lgkmcnt(0)
	s_barrier
	v_mfma_f32_32x32x16_bf16 v[20:35], v[244:247], v[228:231], v[20:35]
	s_cbranch_vccnz .LBB0_2017
	s_cmpk_eq_i32 s2, 0xa00
	s_cbranch_scc1 .LBB0_2027
	s_waitcnt vmcnt(8)
	ds_write_b128 v2, v[36:39]
	ds_write_b128 v2, v[48:51] offset:8192
	ds_write_b128 v2, v[80:83] offset:16384
	ds_write_b128 v2, v[60:63] offset:24576
	ds_write_b128 v2, v[84:87] offset:32768
	ds_write_b128 v2, v[96:99] offset:40960
	ds_write_b128 v2, v[104:107] offset:49152
	ds_write_b128 v2, v[112:115] offset:57344

.LBB0_2675:
	v_add_u32_e32 v156, s7, v188
	v_add_u32_e32 v157, s7, v189
	v_add_u32_e32 v158, v156, v191
	ds_read_b128 v[216:219], v158
	v_add_u32_e32 v159, v157, v191
	ds_read_b128 v[232:235], v159 offset:32768
	ds_read_b128 v[244:247], v159 offset:49152
	v_add_u32_e32 v164, v156, v192
	ds_read_b128 v[220:223], v164
	v_add_u32_e32 v165, v157, v192
	ds_read_b128 v[236:239], v165 offset:32768
	ds_read_b128 v[248:251], v165 offset:49152
	v_add_u32_e32 v180, v156, v193
	ds_read_b128 v[224:227], v180
	v_add_u32_e32 v181, v157, v193
	ds_read_b128 v[240:243], v181 offset:32768
	ds_read_b128 v[176:179], v181 offset:49152
	v_add_u32_e32 v200, v156, v194
	ds_read_b128 v[228:231], v200
	v_add_u32_e32 v201, v157, v194
	s_waitcnt lgkmcnt(8)
	v_mfma_f32_32x32x16_bf16 v[4:19], v[232:235], v[216:219], v[4:19]
	s_waitcnt lgkmcnt(7)
	v_mfma_f32_32x32x16_bf16 v[20:35], v[244:247], v[216:219], v[20:35]
	ds_read_b128 v[232:235], v201 offset:32768
	ds_read_b128 v[244:247], v201 offset:49152
	s_waitcnt lgkmcnt(7)
	v_mfma_f32_32x32x16_bf16 v[4:19], v[236:239], v[220:223], v[4:19]
	s_waitcnt lgkmcnt(6)
	v_mfma_f32_32x32x16_bf16 v[20:35], v[248:251], v[220:223], v[20:35]
	s_waitcnt lgkmcnt(4)
	v_mfma_f32_32x32x16_bf16 v[4:19], v[240:243], v[224:227], v[4:19]
	s_waitcnt lgkmcnt(3)
	v_mfma_f32_32x32x16_bf16 v[20:35], v[176:179], v[224:227], v[20:35]
	s_waitcnt lgkmcnt(1)
	v_mfma_f32_32x32x16_bf16 v[4:19], v[232:235], v[228:231], v[4:19]
	s_waitcnt lgkmcnt(0)
	s_barrier
	v_mfma_f32_32x32x16_bf16 v[20:35], v[244:247], v[228:231], v[20:35]

.LBB0_2679:
	s_add_i32 s7, s7, 0
	v_add_u32_e32 v156, s7, v188
	v_add_u32_e32 v157, s7, v189
	s_cmp_lt_u32 s5, 6
	s_cselect_b64 s[20:21], -1, 0
	s_cmp_gt_u32 s5, 5
	v_add_u32_e32 v158, v156, v191
	ds_read_b128 v[216:219], v158
	v_add_u32_e32 v159, v157, v191
	ds_read_b128 v[232:235], v159 offset:32768
	ds_read_b128 v[244:247], v159 offset:49152
	v_add_u32_e32 v164, v156, v192
	ds_read_b128 v[220:223], v164
	v_add_u32_e32 v165, v157, v192
	ds_read_b128 v[236:239], v165 offset:32768
	ds_read_b128 v[248:251], v165 offset:49152
	v_add_u32_e32 v180, v156, v193
	ds_read_b128 v[224:227], v180
	v_add_u32_e32 v181, v157, v193
	ds_read_b128 v[240:243], v181 offset:32768
	ds_read_b128 v[172:175], v181 offset:49152
	v_add_u32_e32 v200, v156, v194
	ds_read_b128 v[228:231], v200
	v_add_u32_e32 v201, v157, v194
	s_waitcnt lgkmcnt(8)
	v_mfma_f32_32x32x16_bf16 v[4:19], v[232:235], v[216:219], v[4:19]
	s_waitcnt lgkmcnt(7)
	v_mfma_f32_32x32x16_bf16 v[20:35], v[244:247], v[216:219], v[20:35]
	ds_read_b128 v[232:235], v201 offset:32768
	ds_read_b128 v[244:247], v201 offset:49152
	s_waitcnt lgkmcnt(7)
	v_mfma_f32_32x32x16_bf16 v[4:19], v[236:239], v[220:223], v[4:19]
	s_waitcnt lgkmcnt(6)
	v_mfma_f32_32x32x16_bf16 v[20:35], v[248:251], v[220:223], v[20:35]
	s_waitcnt lgkmcnt(4)
	v_mfma_f32_32x32x16_bf16 v[4:19], v[240:243], v[224:227], v[4:19]
	s_waitcnt lgkmcnt(3)
	v_mfma_f32_32x32x16_bf16 v[20:35], v[172:175], v[224:227], v[20:35]
	s_waitcnt lgkmcnt(1)
	v_mfma_f32_32x32x16_bf16 v[4:19], v[232:235], v[228:231], v[4:19]
	s_waitcnt lgkmcnt(0)
	s_barrier
	v_mfma_f32_32x32x16_bf16 v[20:35], v[244:247], v[228:231], v[20:35]
	s_cbranch_scc1 .LBB0_2681
	v_add_u32_e32 v155, s7, v184
	s_waitcnt vmcnt(8)
	ds_write_b128 v155, v[84:87]
	ds_write_b128 v155, v[96:99] offset:8192
	ds_write_b128 v155, v[108:111] offset:16384
	ds_write_b128 v155, v[112:115] offset:24576
	ds_write_b128 v155, v[116:119] offset:32768
	ds_write_b128 v155, v[120:123] offset:40960
	ds_write_b128 v155, v[124:127] offset:49152
	ds_write_b128 v155, v[128:131] offset:57344

.LBB0_2683:
	v_add_u32_e32 v155, s6, v188
	v_add_u32_e32 v156, s6, v189
	s_andn2_b64 vcc, exec, s[20:21]
	v_add_u32_e32 v158, v155, v191
	ds_read_b128 v[216:219], v158
	v_add_u32_e32 v159, v156, v191
	ds_read_b128 v[232:235], v159 offset:32768
	ds_read_b128 v[244:247], v159 offset:49152
	v_add_u32_e32 v164, v155, v192
	ds_read_b128 v[220:223], v164
	v_add_u32_e32 v165, v156, v192
	ds_read_b128 v[236:239], v165 offset:32768
	ds_read_b128 v[248:251], v165 offset:49152
	v_add_u32_e32 v180, v155, v193
	ds_read_b128 v[224:227], v180
	v_add_u32_e32 v181, v156, v193
	ds_read_b128 v[240:243], v181 offset:32768
	ds_read_b128 v[176:179], v181 offset:49152
	v_add_u32_e32 v200, v155, v194
	ds_read_b128 v[228:231], v200
	v_add_u32_e32 v201, v156, v194
	s_waitcnt lgkmcnt(8)
	v_mfma_f32_32x32x16_bf16 v[4:19], v[232:235], v[216:219], v[4:19]
	s_waitcnt lgkmcnt(7)
	v_mfma_f32_32x32x16_bf16 v[20:35], v[244:247], v[216:219], v[20:35]
	ds_read_b128 v[232:235], v201 offset:32768
	ds_read_b128 v[244:247], v201 offset:49152
	s_waitcnt lgkmcnt(7)
	v_mfma_f32_32x32x16_bf16 v[4:19], v[236:239], v[220:223], v[4:19]
	s_waitcnt lgkmcnt(6)
	v_mfma_f32_32x32x16_bf16 v[20:35], v[248:251], v[220:223], v[20:35]
	s_waitcnt lgkmcnt(4)
	v_mfma_f32_32x32x16_bf16 v[4:19], v[240:243], v[224:227], v[4:19]
	s_waitcnt lgkmcnt(3)
	v_mfma_f32_32x32x16_bf16 v[20:35], v[176:179], v[224:227], v[20:35]
	s_waitcnt lgkmcnt(1)
	v_mfma_f32_32x32x16_bf16 v[4:19], v[232:235], v[228:231], v[4:19]
	s_waitcnt lgkmcnt(0)
	s_barrier
	v_mfma_f32_32x32x16_bf16 v[20:35], v[244:247], v[228:231], v[20:35]
	s_cbranch_vccnz .LBB0_2676
	s_cmpk_eq_i32 s12, 0xa00
	s_cbranch_scc1 .LBB0_2686
	s_waitcnt vmcnt(8)
	ds_write_b128 v2, v[36:39]
	ds_write_b128 v2, v[40:43] offset:8192
	ds_write_b128 v2, v[48:51] offset:16384
	ds_write_b128 v2, v[44:47] offset:24576
	ds_write_b128 v2, v[56:59] offset:32768
	ds_write_b128 v2, v[60:63] offset:40960
	ds_write_b128 v2, v[68:71] offset:49152
	ds_write_b128 v2, v[72:75] offset:57344
